# FFN2 weight conversion moved from the scan helper waves to the idle non-scanning WGs at the end of P7 (2-deep pipelined tail)
# speedup vs baseline: 1.0029x; 1.0029x over previous
.LBB0_702:
	s_cmp_lt_i32 s28, 8
	s_cselect_b64 s[4:5], -1, 0
	s_and_b64 s[0:1], s[4:5], s[0:1]
	v_writelane_b32 v255, s0, 15
	s_andn2_b64 vcc, exec, s[0:1]
	s_nop 0
	v_writelane_b32 v255, s1, 16
	s_cbranch_vccnz .LBB0_1054
	s_cmpk_lt_i32 s2, 0x80
	s_cselect_b64 s[0:1], -1, 0
	s_cmpk_lg_i32 s33, 0x100
	s_cselect_b64 s[4:5], -1, 0
	s_or_b64 s[0:1], s[0:1], s[4:5]
	s_cmp_lg_u32 s31, 2
	s_cselect_b64 s[4:5], -1, 0
	v_mov_b32_e32 v1, v0
	s_and_b64 s[0:1], s[0:1], s[4:5]
	s_andn2_b64 vcc, exec, s[0:1]
	v_readfirstlane_b32 s4, v1
	s_cbranch_vccnz .LBB0_836
	s_lshl_b32 s0, s2, 4
	s_and_b32 s0, s0, 0x70
	s_ashr_i32 s1, s2, 3
	s_add_i32 s5, s0, s1
	s_cmpk_eq_i32 s33, 0x100
	s_cselect_b64 s[0:1], -1, 0
	s_and_b64 s[6:7], s[0:1], exec
	s_cselect_b32 s10, s5, s2
	s_cmpk_gt_i32 s10, 0x7f
	s_cbranch_scc1 .LBB0_836
	s_lshl_b32 s5, s2, 2
	s_bfe_u32 s4, s4, 0x20006
	s_or_b32 s4, s5, s4
	s_add_i32 s6, s4, 0x3000
	s_and_b64 s[4:5], s[0:1], exec
	s_mov_b32 s11, 0x10200
	s_add_u32 s12, s92, 0x4100000
	s_addc_u32 s13, s93, 0
	s_add_u32 s16, s92, 0x8100000
	s_addc_u32 s17, s93, 0
	s_add_u32 s18, s92, 0xc100000
	s_addc_u32 s19, s93, 0
	s_add_u32 s14, s92, 0x26e00000
	s_addc_u32 s38, s93, 0
	s_add_u32 s39, s92, 0x22c00000
	s_addc_u32 s72, s93, 0
	s_and_b64 s[0:1], s[0:1], exec
	s_cselect_b32 s68, 0x80, s33
	s_mov_b32 s21, 0
	s_waitcnt vmcnt(0)
	v_mov_b32_e32 v115, 0
	s_movk_i32 s69, 0x500
	s_add_i32 s70, 0, 0x13000
	s_movk_i32 s71, 0x2600
	s_branch .LBB0_707

.LBB0_1053:
	s_cmpk_lg_i32 s33, 0x100
	s_cbranch_scc1 .Lcv_done
	s_cmpk_lt_i32 s2, 0x80
	s_cbranch_scc1 .Lcv_done
	v_readfirstlane_b32 s4, v0
	v_and_b32_e32 v1, 63, v0
	s_lshr_b32 s4, s4, 6
	s_sub_i32 s5, s2, 0x80
	s_lshl_b32 s5, s5, 3
	s_add_i32 s5, s5, s4
	v_lshrrev_b32_e32 v2, 3, v1
	v_and_b32_e32 v3, 7, v1
	s_lshl_b32 s6, s4, 14
	v_mul_u32_u24_e32 v4, 33, v2
	v_lshl_add_u32 v4, v3, 2, v4
	v_lshl_add_u32 v4, v4, 2, s6
	v_mul_u32_u24_e32 v5, 0x108, v3
	v_add_u32_e32 v5, v5, v2
	v_lshl_add_u32 v5, v5, 2, s6
	v_lshlrev_b32_e32 v78, 4, v3
	v_readlane_b32 s8, v254, 7
	v_readlane_b32 s9, v254, 8
	v_readlane_b32 s10, v254, 9
	v_readlane_b32 s11, v254, 10
	v_readlane_b32 s12, v254, 11
	v_readlane_b32 s13, v254, 12
	s_add_u32 s14, s92, 0x4b800000
	s_addc_u32 s15, s93, 0
	s_add_u32 s36, s92, 0x10300000
	s_addc_u32 s37, s93, 0
	s_mov_b32 s38, 0
	s_cmp_lt_u32 s5, 0x200
	s_movk_i32 s7, 0x2c00
	s_cselect_b32 s7, 0x3000, s7
	s_add_i32 s7, s7, s5
	s_add_i32 s7, s7, 0xd000
	s_cmp_lt_u32 s38, 31
	s_cbranch_scc0 .Lcv_dec_d0
	s_lshl_b32 s39, s38, 10
	s_add_i32 s39, s39, s5
	s_add_i32 s39, s39, 0x3000
	s_mov_b32 s58, 1
	s_cmp_ge_u32 s39, 0x5600
	s_cselect_b32 s43, 0x5600, 0
	s_cselect_b32 s40, s10, s8
	s_cselect_b32 s41, s11, s9
	s_cselect_b32 s42, 0x80, 0
	s_sub_i32 s39, s39, s43
	s_mul_hi_u32 s43, s39, 0x2fa0be83
	s_lshr_b32 s43, s43, 6
	s_mul_i32 s44, s43, 0x158
	s_sub_i32 s44, s39, s44
	s_lshl_b32 s45, s43, 6
	s_lshl_b32 s46, s44, 5
	s_mul_i32 s47, s45, 0x2b00
	s_add_i32 s47, s47, s46
	s_lshl_b32 s47, s47, 2
	s_add_u32 s40, s40, s47
	s_addc_u32 s41, s41, 0
	s_lshr_b32 s48, s46, 7
	s_lshl_b32 s48, s48, 8
	s_and_b32 s49, s46, 0x7f
	s_add_i32 s48, s48, s49
	s_add_i32 s48, s48, s42
	s_lshl_b32 s48, s48, 12
	s_add_i32 s48, s48, s45
	s_lshl_b32 s48, s48, 1
	s_add_u32 s50, s14, s48
	s_addc_u32 s51, s15, 0
	s_mov_b32 s53, 0x56000
	s_mov_b32 s52, 0x10000
	s_mov_b32 s57, 0xac00
	s_movk_i32 s47, 0x2000
	s_branch .Lcv_dec_e0
.Lcv_dec_d0:
	s_sub_i32 s39, s38, 31
	s_lshl_b32 s39, s39, 10
	s_add_i32 s39, s39, s5
	s_add_i32 s39, s39, 0xd000
	s_cmp_le_u32 s39, s7
	s_cselect_b32 s58, 1, 0
	s_min_u32 s39, s39, s7
	s_sub_i32 s39, s39, 0xac00
	s_lshr_b32 s43, s39, 7
	s_and_b32 s44, s39, 0x7f
	s_lshl_b32 s45, s43, 6
	s_lshl_b32 s46, s44, 5
	s_lshl_b32 s47, s45, 12
	s_add_i32 s47, s47, s46
	s_lshl_b32 s47, s47, 2
	s_add_u32 s40, s12, s47
	s_addc_u32 s41, s13, 0
	s_mul_i32 s48, s46, 0x2b00
	s_add_i32 s48, s48, s45
	s_lshl_b32 s48, s48, 1
	s_add_u32 s50, s36, s48
	s_addc_u32 s51, s37, 0
	s_mov_b32 s53, 0x20000
	s_mov_b32 s52, 0x2b000
	s_movk_i32 s57, 0x4000
	s_movk_i32 s47, 0x5600
.Lcv_dec_e0:
	v_mad_u32_u24 v75, v2, s57, v78
	v_mad_u32_u24 v76, v2, s47, v78
	s_addk_i32 s38, 1
	global_load_dwordx4 v[10:13], v75, s[40:41]
	s_add_u32 s40, s40, s53
	s_addc_u32 s41, s41, 0
	global_load_dwordx4 v[14:17], v75, s[40:41]
	s_add_u32 s40, s40, s53
	s_addc_u32 s41, s41, 0
	global_load_dwordx4 v[18:21], v75, s[40:41]
	s_add_u32 s40, s40, s53
	s_addc_u32 s41, s41, 0
	global_load_dwordx4 v[22:25], v75, s[40:41]
	s_add_u32 s40, s40, s53
	s_addc_u32 s41, s41, 0
	global_load_dwordx4 v[26:29], v75, s[40:41]
	s_add_u32 s40, s40, s53
	s_addc_u32 s41, s41, 0
	global_load_dwordx4 v[30:33], v75, s[40:41]
	s_add_u32 s40, s40, s53
	s_addc_u32 s41, s41, 0
	global_load_dwordx4 v[34:37], v75, s[40:41]
	s_add_u32 s40, s40, s53
	s_addc_u32 s41, s41, 0
	global_load_dwordx4 v[38:41], v75, s[40:41]
	s_cmp_lt_u32 s38, 31
	s_cbranch_scc0 .Lcv_dec_d1
	s_lshl_b32 s39, s38, 10
	s_add_i32 s39, s39, s5
	s_add_i32 s39, s39, 0x3000
	s_mov_b32 s59, 1
	s_cmp_ge_u32 s39, 0x5600
	s_cselect_b32 s43, 0x5600, 0
	s_cselect_b32 s40, s10, s8
	s_cselect_b32 s41, s11, s9
	s_cselect_b32 s42, 0x80, 0
	s_sub_i32 s39, s39, s43
	s_mul_hi_u32 s43, s39, 0x2fa0be83
	s_lshr_b32 s43, s43, 6
	s_mul_i32 s44, s43, 0x158
	s_sub_i32 s44, s39, s44
	s_lshl_b32 s45, s43, 6
	s_lshl_b32 s46, s44, 5
	s_mul_i32 s47, s45, 0x2b00
	s_add_i32 s47, s47, s46
	s_lshl_b32 s47, s47, 2
	s_add_u32 s40, s40, s47
	s_addc_u32 s41, s41, 0
	s_lshr_b32 s48, s46, 7
	s_lshl_b32 s48, s48, 8
	s_and_b32 s49, s46, 0x7f
	s_add_i32 s48, s48, s49
	s_add_i32 s48, s48, s42
	s_lshl_b32 s48, s48, 12
	s_add_i32 s48, s48, s45
	s_lshl_b32 s48, s48, 1
	s_add_u32 s54, s14, s48
	s_addc_u32 s55, s15, 0
	s_mov_b32 s53, 0x56000
	s_mov_b32 s56, 0x10000
	s_mov_b32 s57, 0xac00
	s_movk_i32 s47, 0x2000
	s_branch .Lcv_dec_e1
.Lcv_dec_d1:
	s_sub_i32 s39, s38, 31
	s_lshl_b32 s39, s39, 10
	s_add_i32 s39, s39, s5
	s_add_i32 s39, s39, 0xd000
	s_cmp_le_u32 s39, s7
	s_cselect_b32 s59, 1, 0
	s_min_u32 s39, s39, s7
	s_sub_i32 s39, s39, 0xac00
	s_lshr_b32 s43, s39, 7
	s_and_b32 s44, s39, 0x7f
	s_lshl_b32 s45, s43, 6
	s_lshl_b32 s46, s44, 5
	s_lshl_b32 s47, s45, 12
	s_add_i32 s47, s47, s46
	s_lshl_b32 s47, s47, 2
	s_add_u32 s40, s12, s47
	s_addc_u32 s41, s13, 0
	s_mul_i32 s48, s46, 0x2b00
	s_add_i32 s48, s48, s45
	s_lshl_b32 s48, s48, 1
	s_add_u32 s54, s36, s48
	s_addc_u32 s55, s37, 0
	s_mov_b32 s53, 0x20000
	s_mov_b32 s56, 0x2b000
	s_movk_i32 s57, 0x4000
	s_movk_i32 s47, 0x5600
.Lcv_dec_e1:
	v_mad_u32_u24 v75, v2, s57, v78
	v_mad_u32_u24 v77, v2, s47, v78
	s_addk_i32 s38, 1
	global_load_dwordx4 v[80:83], v75, s[40:41]
	s_add_u32 s40, s40, s53
	s_addc_u32 s41, s41, 0
	global_load_dwordx4 v[84:87], v75, s[40:41]
	s_add_u32 s40, s40, s53
	s_addc_u32 s41, s41, 0
	global_load_dwordx4 v[88:91], v75, s[40:41]
	s_add_u32 s40, s40, s53
	s_addc_u32 s41, s41, 0
	global_load_dwordx4 v[92:95], v75, s[40:41]
	s_add_u32 s40, s40, s53
	s_addc_u32 s41, s41, 0
	global_load_dwordx4 v[96:99], v75, s[40:41]
	s_add_u32 s40, s40, s53
	s_addc_u32 s41, s41, 0
	global_load_dwordx4 v[100:103], v75, s[40:41]
	s_add_u32 s40, s40, s53
	s_addc_u32 s41, s41, 0
	global_load_dwordx4 v[104:107], v75, s[40:41]
	s_add_u32 s40, s40, s53
	s_addc_u32 s41, s41, 0
	global_load_dwordx4 v[108:111], v75, s[40:41]
	s_waitcnt vmcnt(8)
.Lcv_loop:
	v_mov_b32_e32 v74, v4
	ds_write2_b32 v74, v10, v11 offset1:1
	ds_write2_b32 v74, v12, v13 offset0:2 offset1:3
	v_add_u32_e32 v74, 0x420, v74
	ds_write2_b32 v74, v14, v15 offset1:1
	ds_write2_b32 v74, v16, v17 offset0:2 offset1:3
	v_add_u32_e32 v74, 0x420, v74
	ds_write2_b32 v74, v18, v19 offset1:1
	ds_write2_b32 v74, v20, v21 offset0:2 offset1:3
	v_add_u32_e32 v74, 0x420, v74
	ds_write2_b32 v74, v22, v23 offset1:1
	ds_write2_b32 v74, v24, v25 offset0:2 offset1:3
	v_add_u32_e32 v74, 0x420, v74
	ds_write2_b32 v74, v26, v27 offset1:1
	ds_write2_b32 v74, v28, v29 offset0:2 offset1:3
	v_add_u32_e32 v74, 0x420, v74
	ds_write2_b32 v74, v30, v31 offset1:1
	ds_write2_b32 v74, v32, v33 offset0:2 offset1:3
	v_add_u32_e32 v74, 0x420, v74
	ds_write2_b32 v74, v34, v35 offset1:1
	ds_write2_b32 v74, v36, v37 offset0:2 offset1:3
	v_add_u32_e32 v74, 0x420, v74
	ds_write2_b32 v74, v38, v39 offset1:1
	ds_write2_b32 v74, v40, v41 offset0:2 offset1:3
	s_waitcnt lgkmcnt(0)
	ds_read2_b32 v[42:43], v5 offset0:0 offset1:33
	ds_read2_b32 v[44:45], v5 offset0:66 offset1:99
	ds_read2_b32 v[46:47], v5 offset0:132 offset1:165
	ds_read2_b32 v[48:49], v5 offset0:198 offset1:231
	ds_read2_b32 v[50:51], v5 offset0:8 offset1:41
	ds_read2_b32 v[52:53], v5 offset0:74 offset1:107
	ds_read2_b32 v[54:55], v5 offset0:140 offset1:173
	ds_read2_b32 v[56:57], v5 offset0:206 offset1:239
	ds_read2_b32 v[58:59], v5 offset0:16 offset1:49
	ds_read2_b32 v[60:61], v5 offset0:82 offset1:115
	ds_read2_b32 v[62:63], v5 offset0:148 offset1:181
	ds_read2_b32 v[64:65], v5 offset0:214 offset1:247
	ds_read2_b32 v[66:67], v5 offset0:24 offset1:57
	ds_read2_b32 v[68:69], v5 offset0:90 offset1:123
	ds_read2_b32 v[70:71], v5 offset0:156 offset1:189
	ds_read2_b32 v[72:73], v5 offset0:222 offset1:255
	s_waitcnt lgkmcnt(0)
	v_cvt_pk_bf16_f32 v112, v42, v43
	v_cvt_pk_bf16_f32 v113, v44, v45
	v_cvt_pk_bf16_f32 v114, v46, v47
	v_cvt_pk_bf16_f32 v115, v48, v49
	v_cvt_pk_bf16_f32 v116, v50, v51
	v_cvt_pk_bf16_f32 v117, v52, v53
	v_cvt_pk_bf16_f32 v118, v54, v55
	v_cvt_pk_bf16_f32 v119, v56, v57
	v_cvt_pk_bf16_f32 v120, v58, v59
	v_cvt_pk_bf16_f32 v121, v60, v61
	v_cvt_pk_bf16_f32 v122, v62, v63
	v_cvt_pk_bf16_f32 v123, v64, v65
	v_cvt_pk_bf16_f32 v124, v66, v67
	v_cvt_pk_bf16_f32 v125, v68, v69
	v_cvt_pk_bf16_f32 v126, v70, v71
	v_cvt_pk_bf16_f32 v127, v72, v73
	s_nop 1
	global_store_dwordx4 v76, v[112:115], s[50:51]
	s_add_u32 s50, s50, s52
	s_addc_u32 s51, s51, 0
	global_store_dwordx4 v76, v[116:119], s[50:51]
	s_add_u32 s50, s50, s52
	s_addc_u32 s51, s51, 0
	global_store_dwordx4 v76, v[120:123], s[50:51]
	s_add_u32 s50, s50, s52
	s_addc_u32 s51, s51, 0
	global_store_dwordx4 v76, v[124:127], s[50:51]
	s_cmp_lt_u32 s38, 31
	s_cbranch_scc0 .Lcv_dec_d2
	s_lshl_b32 s39, s38, 10
	s_add_i32 s39, s39, s5
	s_add_i32 s39, s39, 0x3000
	s_mov_b32 s58, 1
	s_cmp_ge_u32 s39, 0x5600
	s_cselect_b32 s43, 0x5600, 0
	s_cselect_b32 s40, s10, s8
	s_cselect_b32 s41, s11, s9
	s_cselect_b32 s42, 0x80, 0
	s_sub_i32 s39, s39, s43
	s_mul_hi_u32 s43, s39, 0x2fa0be83
	s_lshr_b32 s43, s43, 6
	s_mul_i32 s44, s43, 0x158
	s_sub_i32 s44, s39, s44
	s_lshl_b32 s45, s43, 6
	s_lshl_b32 s46, s44, 5
	s_mul_i32 s47, s45, 0x2b00
	s_add_i32 s47, s47, s46
	s_lshl_b32 s47, s47, 2
	s_add_u32 s40, s40, s47
	s_addc_u32 s41, s41, 0
	s_lshr_b32 s48, s46, 7
	s_lshl_b32 s48, s48, 8
	s_and_b32 s49, s46, 0x7f
	s_add_i32 s48, s48, s49
	s_add_i32 s48, s48, s42
	s_lshl_b32 s48, s48, 12
	s_add_i32 s48, s48, s45
	s_lshl_b32 s48, s48, 1
	s_add_u32 s50, s14, s48
	s_addc_u32 s51, s15, 0
	s_mov_b32 s53, 0x56000
	s_mov_b32 s52, 0x10000
	s_mov_b32 s57, 0xac00
	s_movk_i32 s47, 0x2000
	s_branch .Lcv_dec_e2

.Lcv_dec_e2:
	v_mad_u32_u24 v75, v2, s57, v78
	v_mad_u32_u24 v76, v2, s47, v78
	s_addk_i32 s38, 1
	global_load_dwordx4 v[10:13], v75, s[40:41]
	s_add_u32 s40, s40, s53
	s_addc_u32 s41, s41, 0
	global_load_dwordx4 v[14:17], v75, s[40:41]
	s_add_u32 s40, s40, s53
	s_addc_u32 s41, s41, 0
	global_load_dwordx4 v[18:21], v75, s[40:41]
	s_add_u32 s40, s40, s53
	s_addc_u32 s41, s41, 0
	global_load_dwordx4 v[22:25], v75, s[40:41]
	s_add_u32 s40, s40, s53
	s_addc_u32 s41, s41, 0
	global_load_dwordx4 v[26:29], v75, s[40:41]
	s_add_u32 s40, s40, s53
	s_addc_u32 s41, s41, 0
	global_load_dwordx4 v[30:33], v75, s[40:41]
	s_add_u32 s40, s40, s53
	s_addc_u32 s41, s41, 0
	global_load_dwordx4 v[34:37], v75, s[40:41]
	s_add_u32 s40, s40, s53
	s_addc_u32 s41, s41, 0
	global_load_dwordx4 v[38:41], v75, s[40:41]
	s_waitcnt vmcnt(12)
	s_cmp_eq_u32 s59, 0
	s_cbranch_scc1 .Lcv_done
	v_mov_b32_e32 v74, v4
	ds_write2_b32 v74, v80, v81 offset1:1
	ds_write2_b32 v74, v82, v83 offset0:2 offset1:3
	v_add_u32_e32 v74, 0x420, v74
	ds_write2_b32 v74, v84, v85 offset1:1
	ds_write2_b32 v74, v86, v87 offset0:2 offset1:3
	v_add_u32_e32 v74, 0x420, v74
	ds_write2_b32 v74, v88, v89 offset1:1
	ds_write2_b32 v74, v90, v91 offset0:2 offset1:3
	v_add_u32_e32 v74, 0x420, v74
	ds_write2_b32 v74, v92, v93 offset1:1
	ds_write2_b32 v74, v94, v95 offset0:2 offset1:3
	v_add_u32_e32 v74, 0x420, v74
	ds_write2_b32 v74, v96, v97 offset1:1
	ds_write2_b32 v74, v98, v99 offset0:2 offset1:3
	v_add_u32_e32 v74, 0x420, v74
	ds_write2_b32 v74, v100, v101 offset1:1
	ds_write2_b32 v74, v102, v103 offset0:2 offset1:3
	v_add_u32_e32 v74, 0x420, v74
	ds_write2_b32 v74, v104, v105 offset1:1
	ds_write2_b32 v74, v106, v107 offset0:2 offset1:3
	v_add_u32_e32 v74, 0x420, v74
	ds_write2_b32 v74, v108, v109 offset1:1
	ds_write2_b32 v74, v110, v111 offset0:2 offset1:3
	s_waitcnt lgkmcnt(0)
	ds_read2_b32 v[42:43], v5 offset0:0 offset1:33
	ds_read2_b32 v[44:45], v5 offset0:66 offset1:99
	ds_read2_b32 v[46:47], v5 offset0:132 offset1:165
	ds_read2_b32 v[48:49], v5 offset0:198 offset1:231
	ds_read2_b32 v[50:51], v5 offset0:8 offset1:41
	ds_read2_b32 v[52:53], v5 offset0:74 offset1:107
	ds_read2_b32 v[54:55], v5 offset0:140 offset1:173
	ds_read2_b32 v[56:57], v5 offset0:206 offset1:239
	ds_read2_b32 v[58:59], v5 offset0:16 offset1:49
	ds_read2_b32 v[60:61], v5 offset0:82 offset1:115
	ds_read2_b32 v[62:63], v5 offset0:148 offset1:181
	ds_read2_b32 v[64:65], v5 offset0:214 offset1:247
	ds_read2_b32 v[66:67], v5 offset0:24 offset1:57
	ds_read2_b32 v[68:69], v5 offset0:90 offset1:123
	ds_read2_b32 v[70:71], v5 offset0:156 offset1:189
	ds_read2_b32 v[72:73], v5 offset0:222 offset1:255
	s_waitcnt lgkmcnt(0)
	v_cvt_pk_bf16_f32 v112, v42, v43
	v_cvt_pk_bf16_f32 v113, v44, v45
	v_cvt_pk_bf16_f32 v114, v46, v47
	v_cvt_pk_bf16_f32 v115, v48, v49
	v_cvt_pk_bf16_f32 v116, v50, v51
	v_cvt_pk_bf16_f32 v117, v52, v53
	v_cvt_pk_bf16_f32 v118, v54, v55
	v_cvt_pk_bf16_f32 v119, v56, v57
	v_cvt_pk_bf16_f32 v120, v58, v59
	v_cvt_pk_bf16_f32 v121, v60, v61
	v_cvt_pk_bf16_f32 v122, v62, v63
	v_cvt_pk_bf16_f32 v123, v64, v65
	v_cvt_pk_bf16_f32 v124, v66, v67
	v_cvt_pk_bf16_f32 v125, v68, v69
	v_cvt_pk_bf16_f32 v126, v70, v71
	v_cvt_pk_bf16_f32 v127, v72, v73
	s_nop 1
	global_store_dwordx4 v77, v[112:115], s[54:55]
	s_add_u32 s54, s54, s56
	s_addc_u32 s55, s55, 0
	global_store_dwordx4 v77, v[116:119], s[54:55]
	s_add_u32 s54, s54, s56
	s_addc_u32 s55, s55, 0
	global_store_dwordx4 v77, v[120:123], s[54:55]
	s_add_u32 s54, s54, s56
	s_addc_u32 s55, s55, 0
	global_store_dwordx4 v77, v[124:127], s[54:55]
	s_cmp_lt_u32 s38, 31
	s_cbranch_scc0 .Lcv_dec_d3
	s_lshl_b32 s39, s38, 10
	s_add_i32 s39, s39, s5
	s_add_i32 s39, s39, 0x3000
	s_mov_b32 s59, 1
	s_cmp_ge_u32 s39, 0x5600
	s_cselect_b32 s43, 0x5600, 0
	s_cselect_b32 s40, s10, s8
	s_cselect_b32 s41, s11, s9
	s_cselect_b32 s42, 0x80, 0
	s_sub_i32 s39, s39, s43
	s_mul_hi_u32 s43, s39, 0x2fa0be83
	s_lshr_b32 s43, s43, 6
	s_mul_i32 s44, s43, 0x158
	s_sub_i32 s44, s39, s44
	s_lshl_b32 s45, s43, 6
	s_lshl_b32 s46, s44, 5
	s_mul_i32 s47, s45, 0x2b00
	s_add_i32 s47, s47, s46
	s_lshl_b32 s47, s47, 2
	s_add_u32 s40, s40, s47
	s_addc_u32 s41, s41, 0
	s_lshr_b32 s48, s46, 7
	s_lshl_b32 s48, s48, 8
	s_and_b32 s49, s46, 0x7f
	s_add_i32 s48, s48, s49
	s_add_i32 s48, s48, s42
	s_lshl_b32 s48, s48, 12
	s_add_i32 s48, s48, s45
	s_lshl_b32 s48, s48, 1
	s_add_u32 s54, s14, s48
	s_addc_u32 s55, s15, 0
	s_mov_b32 s53, 0x56000
	s_mov_b32 s56, 0x10000
	s_mov_b32 s57, 0xac00
	s_movk_i32 s47, 0x2000
	s_branch .Lcv_dec_e3

.Lcv_dec_e3:
	v_mad_u32_u24 v75, v2, s57, v78
	v_mad_u32_u24 v77, v2, s47, v78
	s_addk_i32 s38, 1
	global_load_dwordx4 v[80:83], v75, s[40:41]
	s_add_u32 s40, s40, s53
	s_addc_u32 s41, s41, 0
	global_load_dwordx4 v[84:87], v75, s[40:41]
	s_add_u32 s40, s40, s53
	s_addc_u32 s41, s41, 0
	global_load_dwordx4 v[88:91], v75, s[40:41]
	s_add_u32 s40, s40, s53
	s_addc_u32 s41, s41, 0
	global_load_dwordx4 v[92:95], v75, s[40:41]
	s_add_u32 s40, s40, s53
	s_addc_u32 s41, s41, 0
	global_load_dwordx4 v[96:99], v75, s[40:41]
	s_add_u32 s40, s40, s53
	s_addc_u32 s41, s41, 0
	global_load_dwordx4 v[100:103], v75, s[40:41]
	s_add_u32 s40, s40, s53
	s_addc_u32 s41, s41, 0
	global_load_dwordx4 v[104:107], v75, s[40:41]
	s_add_u32 s40, s40, s53
	s_addc_u32 s41, s41, 0
	global_load_dwordx4 v[108:111], v75, s[40:41]
	s_waitcnt vmcnt(12)
	s_cmp_lg_u32 s58, 0
	s_cbranch_scc1 .Lcv_loop
.Lcv_done:
	s_waitcnt vmcnt(0)
	v_readlane_b32 s28, v255, 5
	v_readlane_b32 s86, v254, 33
	v_readlane_b32 s29, v255, 6
	v_readlane_b32 s84, v255, 17
	v_readlane_b32 s87, v254, 34
	v_readlane_b32 s30, v255, 7
	v_readlane_b32 s31, v255, 8
	v_readlane_b32 s85, v255, 18
